# indexer select: key load and mask build at wave priority 1, threshold loop at 0
# speedup vs baseline: 1.2560x; 1.0058x over previous
.LBB0_644:
	s_setprio 1
	s_add_i32 s30, s29, s28
	v_lshl_or_b32 v44, s30, 13, v120
	ds_read_u16 v41, v44
	ds_read_u16 v39, v44 offset:128
	ds_read_u16 v38, v44 offset:256
	ds_read_u16 v37, v44 offset:384
	s_add_i32 s29, s30, s53
	s_lshl_b32 s30, s30, 12
	ds_read_u16 v1, v44 offset:512
	ds_read_u16 v0, v44 offset:640
	ds_read_u16 v3, v44 offset:768
	ds_read_u16 v2, v44 offset:896
	ds_read_u16 v5, v44 offset:1024
	ds_read_u16 v4, v44 offset:1152
	ds_read_u16 v7, v44 offset:1280
	ds_read_u16 v6, v44 offset:1408
	ds_read_u16 v9, v44 offset:1536
	ds_read_u16 v8, v44 offset:1664
	ds_read_u16 v11, v44 offset:1792
	s_waitcnt lgkmcnt(10)
	s_movk_i32 s38, 0xeff
	v_lshlrev_b32_e32 v1, 12, v1
	v_bitop3_b32 v1, v1, s38, v106 bitop3:0x36
	v_cmp_ge_u32_e32 vcc, s29, v142
	v_lshl_add_u32 v10, s30, 1, v204
	ds_read_u16 v10, v10
	s_waitcnt lgkmcnt(10)
	s_movk_i32 s38, 0xebf
	v_lshlrev_b32_e32 v0, 12, v0
	v_bitop3_b32 v0, v0, s38, v106 bitop3:0x36
	v_cndmask_b32_e32 v1, 0, v1, vcc
	v_cmp_ge_u32_e32 vcc, s29, v143
	ds_read_u16 v13, v44 offset:2048
	s_waitcnt lgkmcnt(10)
	s_movk_i32 s38, 0xe7f
	v_lshlrev_b32_e32 v3, 12, v3
	v_bitop3_b32 v3, v3, s38, v106 bitop3:0x36
	v_cndmask_b32_e32 v0, 0, v0, vcc
	v_cmp_ge_u32_e32 vcc, s29, v144
	ds_read_u16 v12, v44 offset:2176
	s_waitcnt lgkmcnt(10)
	s_movk_i32 s38, 0xe3f
	v_lshlrev_b32_e32 v2, 12, v2
	v_bitop3_b32 v2, v2, s38, v106 bitop3:0x36
	v_cndmask_b32_e32 v3, 0, v3, vcc
	v_cmp_ge_u32_e32 vcc, s29, v145
	ds_read_u16 v15, v44 offset:2304
	s_waitcnt lgkmcnt(10)
	s_movk_i32 s38, 0xdff
	v_lshlrev_b32_e32 v5, 12, v5
	v_bitop3_b32 v5, v5, s38, v106 bitop3:0x36
	v_cndmask_b32_e32 v2, 0, v2, vcc
	v_cmp_ge_u32_e32 vcc, s29, v146
	ds_read_u16 v14, v44 offset:2432
	s_waitcnt lgkmcnt(10)
	s_movk_i32 s38, 0xdbf
	v_lshlrev_b32_e32 v4, 12, v4
	v_bitop3_b32 v4, v4, s38, v106 bitop3:0x36
	v_cndmask_b32_e32 v5, 0, v5, vcc
	v_cmp_ge_u32_e32 vcc, s29, v147
	ds_read_u16 v17, v44 offset:2560
	s_waitcnt lgkmcnt(10)
	s_movk_i32 s38, 0xd7f
	v_lshlrev_b32_e32 v7, 12, v7
	v_bitop3_b32 v7, v7, s38, v106 bitop3:0x36
	v_cndmask_b32_e32 v4, 0, v4, vcc
	v_cmp_ge_u32_e32 vcc, s29, v148
	ds_read_u16 v16, v44 offset:2688
	s_waitcnt lgkmcnt(10)
	s_movk_i32 s38, 0xd3f
	v_lshlrev_b32_e32 v6, 12, v6
	v_bitop3_b32 v6, v6, s38, v106 bitop3:0x36
	v_cndmask_b32_e32 v7, 0, v7, vcc
	v_cmp_ge_u32_e32 vcc, s29, v149
	ds_read_u16 v19, v44 offset:2816
	s_waitcnt lgkmcnt(10)
	s_movk_i32 s38, 0xcff
	v_lshlrev_b32_e32 v9, 12, v9
	v_bitop3_b32 v9, v9, s38, v106 bitop3:0x36
	v_cndmask_b32_e32 v6, 0, v6, vcc
	v_cmp_ge_u32_e32 vcc, s29, v150
	ds_read_u16 v18, v44 offset:2944
	s_waitcnt lgkmcnt(10)
	s_movk_i32 s38, 0xcbf
	v_lshlrev_b32_e32 v8, 12, v8
	v_bitop3_b32 v8, v8, s38, v106 bitop3:0x36
	v_cndmask_b32_e32 v9, 0, v9, vcc
	v_cmp_ge_u32_e32 vcc, s29, v151
	ds_read_u16 v21, v44 offset:3072
	s_waitcnt lgkmcnt(10)
	s_movk_i32 s38, 0xc7f
	v_lshlrev_b32_e32 v11, 12, v11
	v_bitop3_b32 v11, v11, s38, v106 bitop3:0x36
	v_cndmask_b32_e32 v8, 0, v8, vcc
	v_cmp_ge_u32_e32 vcc, s29, v152
	ds_read_u16 v20, v44 offset:3200
	s_waitcnt lgkmcnt(10)
	v_lshlrev_b32_e32 v10, 12, v10
	v_bitop3_b32 v10, v10, s48, v153 bitop3:0x36
	v_cndmask_b32_e32 v11, 0, v11, vcc
	v_cmp_ge_u32_e32 vcc, s29, v153
	ds_read_u16 v23, v44 offset:3328
	s_waitcnt lgkmcnt(10)
	s_movk_i32 s38, 0xbff
	v_lshlrev_b32_e32 v13, 12, v13
	v_bitop3_b32 v13, v13, s38, v106 bitop3:0x36
	v_cndmask_b32_e32 v10, 0, v10, vcc
	v_cmp_ge_u32_e32 vcc, s29, v154
	ds_read_u16 v22, v44 offset:3456
	s_waitcnt lgkmcnt(10)
	s_movk_i32 s38, 0xbbf
	v_lshlrev_b32_e32 v12, 12, v12
	v_bitop3_b32 v12, v12, s38, v106 bitop3:0x36
	v_cndmask_b32_e32 v13, 0, v13, vcc
	v_cmp_ge_u32_e32 vcc, s29, v155
	ds_read_u16 v25, v44 offset:3584
	s_waitcnt lgkmcnt(10)
	s_movk_i32 s38, 0xb7f
	v_lshlrev_b32_e32 v15, 12, v15
	v_bitop3_b32 v15, v15, s38, v106 bitop3:0x36
	v_cndmask_b32_e32 v12, 0, v12, vcc
	v_cmp_ge_u32_e32 vcc, s29, v156
	ds_read_u16 v24, v44 offset:3712
	s_waitcnt lgkmcnt(10)
	s_movk_i32 s38, 0xb3f
	v_lshlrev_b32_e32 v14, 12, v14
	v_bitop3_b32 v14, v14, s38, v106 bitop3:0x36
	v_cndmask_b32_e32 v15, 0, v15, vcc
	v_cmp_ge_u32_e32 vcc, s29, v157
	ds_read_u16 v27, v44 offset:3840
	s_waitcnt lgkmcnt(10)
	s_movk_i32 s38, 0xaff
	v_lshlrev_b32_e32 v17, 12, v17
	v_bitop3_b32 v17, v17, s38, v106 bitop3:0x36
	v_cndmask_b32_e32 v14, 0, v14, vcc
	v_cmp_ge_u32_e32 vcc, s29, v158
	v_lshl_add_u32 v26, s30, 1, v205
	ds_read_u16 v26, v26
	s_waitcnt lgkmcnt(10)
	s_movk_i32 s38, 0xabf
	v_lshlrev_b32_e32 v16, 12, v16
	v_bitop3_b32 v16, v16, s38, v106 bitop3:0x36
	v_cndmask_b32_e32 v17, 0, v17, vcc
	v_cmp_ge_u32_e32 vcc, s29, v159
	ds_read_u16 v29, v44 offset:4096
	s_waitcnt lgkmcnt(10)
	s_movk_i32 s38, 0xa7f
	v_lshlrev_b32_e32 v19, 12, v19
	v_bitop3_b32 v19, v19, s38, v106 bitop3:0x36
	v_cndmask_b32_e32 v16, 0, v16, vcc
	v_cmp_ge_u32_e32 vcc, s29, v160
	ds_read_u16 v28, v44 offset:4224
	s_waitcnt lgkmcnt(10)
	s_movk_i32 s38, 0xa3f
	v_lshlrev_b32_e32 v18, 12, v18
	v_bitop3_b32 v18, v18, s38, v106 bitop3:0x36
	v_cndmask_b32_e32 v19, 0, v19, vcc
	v_cmp_ge_u32_e32 vcc, s29, v161
	ds_read_u16 v31, v44 offset:4352
	s_waitcnt lgkmcnt(10)
	s_movk_i32 s38, 0x9ff
	v_lshlrev_b32_e32 v21, 12, v21
	v_bitop3_b32 v21, v21, s38, v106 bitop3:0x36
	v_cndmask_b32_e32 v18, 0, v18, vcc
	v_cmp_ge_u32_e32 vcc, s29, v162
	ds_read_u16 v30, v44 offset:4480
	s_waitcnt lgkmcnt(10)
	s_movk_i32 s38, 0x9bf
	v_lshlrev_b32_e32 v20, 12, v20
	v_bitop3_b32 v20, v20, s38, v106 bitop3:0x36
	v_cndmask_b32_e32 v21, 0, v21, vcc
	v_cmp_ge_u32_e32 vcc, s29, v163
	ds_read_u16 v33, v44 offset:4608
	s_waitcnt lgkmcnt(10)
	s_movk_i32 s38, 0x97f
	v_lshlrev_b32_e32 v23, 12, v23
	v_bitop3_b32 v23, v23, s38, v106 bitop3:0x36
	v_cndmask_b32_e32 v20, 0, v20, vcc
	v_cmp_ge_u32_e32 vcc, s29, v166
	ds_read_u16 v32, v44 offset:4736
	s_waitcnt lgkmcnt(10)
	s_movk_i32 s38, 0x93f
	v_lshlrev_b32_e32 v22, 12, v22
	v_bitop3_b32 v22, v22, s38, v106 bitop3:0x36
	v_cndmask_b32_e32 v23, 0, v23, vcc
	v_cmp_ge_u32_e32 vcc, s29, v167
	ds_read_u16 v35, v44 offset:4864
	s_waitcnt lgkmcnt(10)
	s_movk_i32 s38, 0x8ff
	v_lshlrev_b32_e32 v25, 12, v25
	v_bitop3_b32 v25, v25, s38, v106 bitop3:0x36
	v_cndmask_b32_e32 v22, 0, v22, vcc
	v_cmp_ge_u32_e32 vcc, s29, v168
	ds_read_u16 v34, v44 offset:4992
	s_waitcnt lgkmcnt(10)
	s_movk_i32 s38, 0x8bf
	v_lshlrev_b32_e32 v24, 12, v24
	v_bitop3_b32 v24, v24, s38, v106 bitop3:0x36
	v_cndmask_b32_e32 v25, 0, v25, vcc
	v_cmp_ge_u32_e32 vcc, s29, v169
	ds_read_u16 v40, v44 offset:5120
	s_waitcnt lgkmcnt(10)
	s_movk_i32 s38, 0x87f
	v_lshlrev_b32_e32 v27, 12, v27
	v_bitop3_b32 v27, v27, s38, v106 bitop3:0x36
	v_cndmask_b32_e32 v24, 0, v24, vcc
	v_cmp_ge_u32_e32 vcc, s29, v170
	ds_read_u16 v36, v44 offset:5248
	s_waitcnt lgkmcnt(10)
	v_lshlrev_b32_e32 v26, 12, v26
	v_bitop3_b32 v26, v26, s48, v171 bitop3:0x36
	v_cndmask_b32_e32 v27, 0, v27, vcc
	v_cmp_ge_u32_e32 vcc, s29, v171
	ds_read_u16 v43, v44 offset:5376
	s_waitcnt lgkmcnt(10)
	s_movk_i32 s38, 0x7ff
	v_lshlrev_b32_e32 v29, 12, v29
	v_bitop3_b32 v29, v29, s38, v106 bitop3:0x36
	v_cndmask_b32_e32 v26, 0, v26, vcc
	v_cmp_ge_u32_e32 vcc, s29, v172
	ds_read_u16 v42, v44 offset:5504
	s_waitcnt lgkmcnt(10)
	s_movk_i32 s38, 0x7bf
	v_lshlrev_b32_e32 v28, 12, v28
	v_bitop3_b32 v28, v28, s38, v106 bitop3:0x36
	v_cndmask_b32_e32 v29, 0, v29, vcc
	v_cmp_ge_u32_e32 vcc, s29, v173
	ds_read_u16 v46, v44 offset:5632
	s_waitcnt lgkmcnt(10)
	s_movk_i32 s38, 0x77f
	v_lshlrev_b32_e32 v31, 12, v31
	v_bitop3_b32 v31, v31, s38, v106 bitop3:0x36
	v_cndmask_b32_e32 v28, 0, v28, vcc
	v_cmp_ge_u32_e32 vcc, s29, v174
	ds_read_u16 v45, v44 offset:5760
	s_waitcnt lgkmcnt(10)
	s_movk_i32 s38, 0x73f
	v_lshlrev_b32_e32 v30, 12, v30
	v_bitop3_b32 v30, v30, s38, v106 bitop3:0x36
	v_cndmask_b32_e32 v31, 0, v31, vcc
	v_cmp_ge_u32_e32 vcc, s29, v175
	ds_read_u16 v48, v44 offset:5888
	s_waitcnt lgkmcnt(10)
	s_movk_i32 s38, 0x6ff
	v_lshlrev_b32_e32 v33, 12, v33
	v_bitop3_b32 v33, v33, s38, v106 bitop3:0x36
	v_cndmask_b32_e32 v30, 0, v30, vcc
	v_cmp_ge_u32_e32 vcc, s29, v176
	v_lshl_add_u32 v47, s30, 1, v206
	ds_read_u16 v47, v47
	s_waitcnt lgkmcnt(10)
	s_movk_i32 s38, 0x6bf
	v_lshlrev_b32_e32 v32, 12, v32
	v_bitop3_b32 v32, v32, s38, v106 bitop3:0x36
	v_cndmask_b32_e32 v33, 0, v33, vcc
	v_cmp_ge_u32_e32 vcc, s29, v177
	ds_read_u16 v50, v44 offset:6144
	s_waitcnt lgkmcnt(10)
	s_movk_i32 s38, 0x67f
	v_lshlrev_b32_e32 v35, 12, v35
	v_bitop3_b32 v35, v35, s38, v106 bitop3:0x36
	v_cndmask_b32_e32 v32, 0, v32, vcc
	v_cmp_ge_u32_e32 vcc, s29, v178
	ds_read_u16 v49, v44 offset:6272
	s_waitcnt lgkmcnt(10)
	s_movk_i32 s38, 0x63f
	v_lshlrev_b32_e32 v34, 12, v34
	v_bitop3_b32 v34, v34, s38, v106 bitop3:0x36
	v_cndmask_b32_e32 v35, 0, v35, vcc
	v_cmp_ge_u32_e32 vcc, s29, v179
	ds_read_u16 v52, v44 offset:6400
	s_waitcnt lgkmcnt(10)
	s_movk_i32 s38, 0x5ff
	v_lshlrev_b32_e32 v40, 12, v40
	v_bitop3_b32 v40, v40, s38, v106 bitop3:0x36
	v_cndmask_b32_e32 v34, 0, v34, vcc
	v_cmp_ge_u32_e32 vcc, s29, v180
	ds_read_u16 v51, v44 offset:6528
	s_waitcnt lgkmcnt(10)
	s_movk_i32 s38, 0x5bf
	v_lshlrev_b32_e32 v36, 12, v36
	v_bitop3_b32 v36, v36, s38, v106 bitop3:0x36
	v_cndmask_b32_e32 v40, 0, v40, vcc
	v_cmp_ge_u32_e32 vcc, s29, v181
	ds_read_u16 v54, v44 offset:6656
	s_waitcnt lgkmcnt(10)
	s_movk_i32 s38, 0x57f
	v_lshlrev_b32_e32 v43, 12, v43
	v_bitop3_b32 v43, v43, s38, v106 bitop3:0x36
	v_cndmask_b32_e32 v36, 0, v36, vcc
	v_cmp_ge_u32_e32 vcc, s29, v182
	ds_read_u16 v53, v44 offset:6784
	s_waitcnt lgkmcnt(10)
	s_movk_i32 s38, 0x53f
	v_lshlrev_b32_e32 v42, 12, v42
	v_bitop3_b32 v42, v42, s38, v106 bitop3:0x36
	v_cndmask_b32_e32 v43, 0, v43, vcc
	v_cmp_ge_u32_e32 vcc, s29, v183
	ds_read_u16 v56, v44 offset:6912
	s_waitcnt lgkmcnt(10)
	s_movk_i32 s38, 0x4ff
	v_lshlrev_b32_e32 v46, 12, v46
	v_bitop3_b32 v46, v46, s38, v106 bitop3:0x36
	v_cndmask_b32_e32 v42, 0, v42, vcc
	v_cmp_ge_u32_e32 vcc, s29, v184
	ds_read_u16 v55, v44 offset:7040
	s_waitcnt lgkmcnt(10)
	s_movk_i32 s38, 0x4bf
	v_lshlrev_b32_e32 v45, 12, v45
	v_bitop3_b32 v45, v45, s38, v106 bitop3:0x36
	v_cndmask_b32_e32 v46, 0, v46, vcc
	v_cmp_ge_u32_e32 vcc, s29, v185
	ds_read_u16 v58, v44 offset:7168
	s_waitcnt lgkmcnt(10)
	s_movk_i32 s38, 0x47f
	v_lshlrev_b32_e32 v48, 12, v48
	v_bitop3_b32 v48, v48, s38, v106 bitop3:0x36
	v_cndmask_b32_e32 v45, 0, v45, vcc
	v_cmp_ge_u32_e32 vcc, s29, v186
	ds_read_u16 v57, v44 offset:7296
	s_waitcnt lgkmcnt(10)
	v_lshlrev_b32_e32 v47, 12, v47
	v_bitop3_b32 v47, v47, s48, v187 bitop3:0x36
	v_cndmask_b32_e32 v48, 0, v48, vcc
	v_cmp_ge_u32_e32 vcc, s29, v187
	ds_read_u16 v60, v44 offset:7424
	s_waitcnt lgkmcnt(10)
	s_movk_i32 s38, 0x3ff
	v_lshlrev_b32_e32 v50, 12, v50
	v_bitop3_b32 v50, v50, s38, v106 bitop3:0x36
	v_cndmask_b32_e32 v47, 0, v47, vcc
	v_cmp_ge_u32_e32 vcc, s29, v188
	ds_read_u16 v59, v44 offset:7552
	s_waitcnt lgkmcnt(10)
	s_movk_i32 s38, 0x3bf
	v_lshlrev_b32_e32 v49, 12, v49
	v_bitop3_b32 v49, v49, s38, v106 bitop3:0x36
	v_cndmask_b32_e32 v50, 0, v50, vcc
	v_cmp_ge_u32_e32 vcc, s29, v189
	ds_read_u16 v62, v44 offset:7680
	s_waitcnt lgkmcnt(10)
	s_movk_i32 s38, 0x37f
	v_lshlrev_b32_e32 v52, 12, v52
	v_bitop3_b32 v52, v52, s38, v106 bitop3:0x36
	v_cndmask_b32_e32 v49, 0, v49, vcc
	v_cmp_ge_u32_e32 vcc, s29, v190
	ds_read_u16 v61, v44 offset:7808
	s_waitcnt lgkmcnt(10)
	s_movk_i32 s38, 0x33f
	v_lshlrev_b32_e32 v51, 12, v51
	v_bitop3_b32 v51, v51, s38, v106 bitop3:0x36
	v_cndmask_b32_e32 v52, 0, v52, vcc
	v_cmp_ge_u32_e32 vcc, s29, v191
	ds_read_u16 v64, v44 offset:7936
	s_waitcnt lgkmcnt(10)
	s_movk_i32 s38, 0x2ff
	v_lshlrev_b32_e32 v54, 12, v54
	v_bitop3_b32 v54, v54, s38, v106 bitop3:0x36
	v_cndmask_b32_e32 v51, 0, v51, vcc
	v_cmp_ge_u32_e32 vcc, s29, v192
	v_lshl_add_u32 v63, s30, 1, v207
	ds_read_u16 v63, v63
	s_waitcnt lgkmcnt(10)
	s_movk_i32 s38, 0x2bf
	v_lshlrev_b32_e32 v53, 12, v53
	v_bitop3_b32 v53, v53, s38, v106 bitop3:0x36
	v_cndmask_b32_e32 v54, 0, v54, vcc
	v_cmp_ge_u32_e32 vcc, s29, v193
	s_waitcnt lgkmcnt(9)
	s_movk_i32 s38, 0x27f
	v_lshlrev_b32_e32 v56, 12, v56
	v_bitop3_b32 v56, v56, s38, v106 bitop3:0x36
	v_cndmask_b32_e32 v53, 0, v53, vcc
	v_cmp_ge_u32_e32 vcc, s29, v194
	s_waitcnt lgkmcnt(8)
	s_movk_i32 s38, 0x23f
	v_lshlrev_b32_e32 v55, 12, v55
	v_bitop3_b32 v55, v55, s38, v106 bitop3:0x36
	v_cndmask_b32_e32 v56, 0, v56, vcc
	v_cmp_ge_u32_e32 vcc, s29, v195
	s_waitcnt lgkmcnt(7)
	s_movk_i32 s38, 0x1ff
	v_lshlrev_b32_e32 v58, 12, v58
	v_bitop3_b32 v58, v58, s38, v106 bitop3:0x36
	v_cndmask_b32_e32 v55, 0, v55, vcc
	v_cmp_ge_u32_e32 vcc, s29, v196
	s_waitcnt lgkmcnt(6)
	s_movk_i32 s38, 0x1bf
	v_lshlrev_b32_e32 v57, 12, v57
	v_bitop3_b32 v57, v57, s38, v106 bitop3:0x36
	v_cndmask_b32_e32 v58, 0, v58, vcc
	v_cmp_ge_u32_e32 vcc, s29, v197
	s_waitcnt lgkmcnt(5)
	s_movk_i32 s38, 0x17f
	v_lshlrev_b32_e32 v60, 12, v60
	v_bitop3_b32 v60, v60, s38, v106 bitop3:0x36
	v_cndmask_b32_e32 v57, 0, v57, vcc
	v_cmp_ge_u32_e32 vcc, s29, v198
	s_waitcnt lgkmcnt(4)
	s_movk_i32 s38, 0x13f
	v_lshlrev_b32_e32 v59, 12, v59
	v_bitop3_b32 v59, v59, s38, v106 bitop3:0x36
	v_cndmask_b32_e32 v60, 0, v60, vcc
	v_cmp_ge_u32_e32 vcc, s29, v199
	s_waitcnt lgkmcnt(3)
	s_movk_i32 s38, 0xff
	v_lshlrev_b32_e32 v62, 12, v62
	v_bitop3_b32 v62, v62, s38, v106 bitop3:0x36
	v_cndmask_b32_e32 v59, 0, v59, vcc
	v_cmp_ge_u32_e32 vcc, s29, v200
	s_waitcnt lgkmcnt(2)
	s_movk_i32 s38, 0xbf
	v_lshlrev_b32_e32 v61, 12, v61
	v_bitop3_b32 v61, v61, s38, v106 bitop3:0x36
	v_cndmask_b32_e32 v62, 0, v62, vcc
	v_cmp_ge_u32_e32 vcc, s29, v201
	s_waitcnt lgkmcnt(1)
	s_movk_i32 s38, 0x7f
	v_lshlrev_b32_e32 v64, 12, v64
	v_bitop3_b32 v64, v64, s38, v106 bitop3:0x36
	v_cndmask_b32_e32 v61, 0, v61, vcc
	v_cmp_ge_u32_e32 vcc, s29, v202
	s_waitcnt lgkmcnt(0)
	v_lshlrev_b32_e32 v63, 12, v63
	v_bitop3_b32 v63, v63, s48, v203 bitop3:0x36
	v_cndmask_b32_e32 v64, 0, v64, vcc
	v_cmp_ge_u32_e32 vcc, s29, v203
	s_nop 1
	v_cndmask_b32_e32 v63, 0, v63, vcc
.LBB0_764:
	s_or_b64 exec, exec, s[36:37]
	s_xor_b64 s[34:35], s[34:35], -1
	s_cmpk_gt_u32 s29, 0x1ff
	s_cselect_b64 s[36:37], -1, 0
	s_cmpk_gt_u32 s29, 0x3ff
	s_cselect_b64 s[38:39], -1, 0
	s_cmpk_gt_u32 s29, 0x5ff
	s_cselect_b64 s[40:41], -1, 0
	s_cmpk_gt_u32 s29, 0x7ff
	s_waitcnt lgkmcnt(2)
	v_lshlrev_b32_sdwa v39, v223, v39 dst_sel:DWORD dst_unused:UNUSED_PAD src0_sel:DWORD src1_sel:WORD_0
	s_movk_i32 s30, 0xfbf
	s_cselect_b64 s[42:43], -1, 0
	s_cmpk_gt_u32 s29, 0x9ff
	v_bitop3_b32 v39, v39, s30, v106 bitop3:0x36
	s_waitcnt lgkmcnt(1)
	v_lshlrev_b32_sdwa v38, v223, v38 dst_sel:DWORD dst_unused:UNUSED_PAD src0_sel:DWORD src1_sel:WORD_0
	s_movk_i32 s30, 0xf7f
	s_cselect_b64 s[44:45], -1, 0
	s_cmpk_gt_u32 s29, 0xbff
	v_lshlrev_b32_sdwa v41, v223, v41 dst_sel:DWORD dst_unused:UNUSED_PAD src0_sel:DWORD src1_sel:WORD_0
	v_bitop3_b32 v38, v38, s30, v106 bitop3:0x36
	s_waitcnt lgkmcnt(0)
	v_lshlrev_b32_sdwa v37, v223, v37 dst_sel:DWORD dst_unused:UNUSED_PAD src0_sel:DWORD src1_sel:WORD_0
	s_movk_i32 s30, 0xf3f
	s_cselect_b64 s[46:47], -1, 0
	s_cmpk_gt_u32 s29, 0xdff
	v_bitop3_b32 v41, v41, s48, v106 bitop3:0x36
	v_bitop3_b32 v37, v37, s30, v106 bitop3:0x36
	s_cselect_b64 s[48:49], -1, 0
	s_setprio 0
	s_lshr_b32 s57, s29, 9
	s_mov_b32 s58, 0
	s_mov_b32 s59, 27
	s_mov_b32 s60, 0x8000000
	v_mov_b32_e32 v254, 0
	v_mov_b32_e32 v255, 0
	s_cmp_eq_u32 s57, 0
	s_cbranch_scc1 .Lbq1_loop
	s_cmp_eq_u32 s57, 1
	s_cbranch_scc1 .Lbq2_loop
	s_cmp_eq_u32 s57, 2
	s_cbranch_scc1 .Lbq3_loop
	s_cmp_eq_u32 s57, 3
	s_cbranch_scc1 .Lbq4_loop
	s_cmp_eq_u32 s57, 4
	s_cbranch_scc1 .Lbq5_loop
	s_cmp_eq_u32 s57, 5
	s_cbranch_scc1 .Lbq6_loop
	s_cmp_eq_u32 s57, 6
	s_cbranch_scc1 .Lbq7_loop

.Lbq_exit:
	s_setprio 1
	v_mov_b32_e32 v44, s58
	s_branch .LBB0_643
